# prep: half the workgroups run the gain-rows pass before the weight transposes (overlap latency-bound and bandwidth-bound halves)
# speedup vs baseline: 1.0135x; 1.0018x over previous
; #define LAS __attribute__((address_space(3)))
; __device__ __forceinline__ unsigned xb_add(unsigned* p, unsigned v) { return __hip_atomic_fetch_add(p, v, __ATOMIC_RELAXED, __HIP_MEMORY_SCOPE_AGENT); }
; __device__ __forceinline__ unsigned xb_xcc_id() { return (unsigned)__builtin_amdgcn_s_getreg((3 << 11) | 20) & 0xFu; }
; __device__ __forceinline__ XcdBarrier xcd_barrier_post(unsigned* bar, volatile LAS unsigned* st) {
;     XcdBarrier b; b.bar = bar; b.x = xb_xcc_id(); b.st = st;
;     if (threadIdx.x == 0) (void)xb_add(&bar[XB_XCNT(b.x)], 1u);
;     return b;
; }
; __global__ void __launch_bounds__(NWAVES * 64, 2) mk_fwd(Args args) {
;     extern __shared__ __attribute__((aligned(16))) unsigned char lds_raw[];
;     LAS unsigned char* lds = (LAS unsigned char*)lds_raw;
;     typedef const __attribute__((address_space(4))) Args* kargs_t;
;     if (threadIdx.x < 16) ((LAS unsigned*)(lds + BAR_LDS_OFF))[threadIdx.x] = 0u;
;     __syncthreads();
;     const XcdBarrier bar = xcd_barrier_post((unsigned*)(args.ws + WS_BAR), (volatile LAS unsigned*)(lds + BAR_LDS_OFF));
_Z6mk_fwd4Args:
	s_load_dwordx4 s[72:75], s[0:1], 0xb8
	s_mov_b32 s98, 0
	v_and_b32_e32 v211, 0x3ff, v0
	s_mov_b32 s34, s2
	s_mov_b64 s[92:93], s[0:1]
	v_cmp_gt_u32_e32 vcc, 16, v211
	s_and_saveexec_b64 s[0:1], vcc
	v_lshl_add_u32 v1, v211, 2, 0
	v_add_u32_e32 v1, 0x23fc0, v1
	v_mov_b32_e32 v2, 0
	ds_write_b32 v1, v2
	s_or_b64 exec, exec, s[0:1]
	s_waitcnt lgkmcnt(0)
	s_barrier
	s_add_u32 s0, s72, 0x8000
	s_getreg_b32 s2, hwreg(HW_REG_XCC_ID, 0, 4)
	s_addc_u32 s1, s73, 0
	s_and_b32 s6, s2, 15
	v_cmp_eq_u32_e64 s[4:5], 0, v211
	s_mov_b64 s[2:3], exec
	s_nop 0
	v_writelane_b32 v253, s4, 0
	s_nop 1
	v_writelane_b32 v253, s5, 1
	s_and_b64 s[4:5], s[2:3], s[4:5]
	s_mov_b64 exec, s[4:5]
	s_cbranch_execz .LBB0_5
	s_mov_b64 s[4:5], exec
	v_mbcnt_lo_u32_b32 v1, s4, 0
	v_mbcnt_hi_u32_b32 v1, s5, v1
	v_cmp_eq_u32_e32 vcc, 0, v1
	s_and_b64 s[8:9], exec, vcc
	s_mov_b64 exec, s[8:9]
	s_cbranch_execz .LBB0_5
	s_lshl_b32 s7, s6, 8
	s_bcnt1_i32_b64 s4, s[4:5]
	v_mov_b32_e32 v1, s7
	v_mov_b32_e32 v2, s4
	global_atomic_add v1, v2, s[0:1] offset:1024

; #define LAS __attribute__((address_space(3)))
; __global__ void __launch_bounds__(NWAVES * 64, 2) mk_fwd(Args args) {
;     ...
;         if (ph == 0) {
;             LAS float* scr = (LAS float*)(lds + wave * 16384);
;             constexpr int I_IN = 16 * (NIN / 32), I_G = 16 * (NGATE / 32), I_S = 16 * 32, I_UP = 16 * (NUP / 32), I_DN = (DFF / 64) * 32, I_L = I_IN + I_G + 3 * I_S + I_UP + I_DN;
;             for (int it = gw; it < DEPTH * I_L; it += NGW) {
;                 const int l = it / I_L; int r = it - l * I_L; bf16* wl = (bf16*)(ws + WS_W + (size_t)l * WL_STRIDE);
;                 if (r < I_IN) { transpose_item(ap->in[2] + (size_t)l * DM * NIN, DM, NIN, (bf16*)((unsigned char*)wl + WO_IN), false, scr, r, lane); continue; } r -= I_IN;
;                 if (r < I_G) { transpose_item(ap->in[3] + (size_t)l * DM * NGATE, DM, NGATE, (bf16*)((unsigned char*)wl + WO_G), false, scr, r, lane); continue; } r -= I_G;
;                 if (r < I_S) { transpose_item(ap->in[13] + (size_t)l * DM * DM, DM, DM, (bf16*)((unsigned char*)wl + WO_A), false, scr, r, lane); continue; } r -= I_S;
;                 if (r < I_S) { transpose_item(ap->in[14] + (size_t)l * DM * DM, DM, DM, (bf16*)((unsigned char*)wl + WO_B), false, scr, r, lane); continue; } r -= I_S;
;                 if (r < I_S) { transpose_item(ap->in[15] + (size_t)l * DM * DM, DM, DM, (bf16*)((unsigned char*)wl + WO_O), false, scr, r, lane); continue; } r -= I_S;
;                 if (r < I_UP) { transpose_item(ap->in[17] + (size_t)l * DM * NUP, DM, NUP, (bf16*)((unsigned char*)wl + WO_UP), true, scr, r, lane); continue; } r -= I_UP;
;                 transpose_item(ap->in[20] + (size_t)l * DFF * DM, DFF, DM, (bf16*)((unsigned char*)wl + WO_DN), false, scr, r, lane);
;             }
;             for (int m = gw; m < M; m += 4 * NGW) gain_rows4_bf16(x_in, ap->in[1], HB, (float*)(ws + WS_RSS), (size_t)m, (size_t)NGW, lane);
.LBB0_406:
	s_cmp_lg_u32 s98, 0
	s_cbranch_scc1 .Lprep_norm
	s_bitcmp1_b32 s89, 3
	s_cbranch_scc0 .Lprep_norm
	s_mov_b32 s98, 1
	s_mov_b32 s99, s30
	v_readlane_b32 s42, v254, 31
	s_branch .LBB0_447

; __device__ __forceinline__ unsigned pk2(float lo, float hi) { return f2bf(lo) | (f2bf(hi) << 16); }
; __device__ __forceinline__ void gain_rows4_bf16(const float* x, const float* g, bf16* o, float* rss, size_t m, size_t rs, int lane) {
;     f32x4 v[4][4];
; #pragma unroll
;     for (int r = 0; r < 4; ++r) { const f32x4* xr = (const f32x4*)(x + (m + r * rs) * DM) + lane;
; #pragma unroll
;         for (int j = 0; j < 4; ++j) v[r][j] = xr[64 * j]; }
;     const f32x4* gr = (const f32x4*)g + lane; f32x4 gg[4];
; #pragma unroll
;     for (int j = 0; j < 4; ++j) gg[j] = gr[64 * j];
; #pragma unroll
;     for (int r = 0; r < 4; ++r) { float s2 = 0.f; v2u* o8 = (v2u*)(o + (m + r * rs) * DM) + lane;
; #pragma unroll
;         for (int j = 0; j < 4; ++j) { s2 += (v[r][j].x * v[r][j].x + v[r][j].y * v[r][j].y) + (v[r][j].z * v[r][j].z + v[r][j].w * v[r][j].w);
;             v2u w; w.x = pk2(v[r][j].x * gg[j].x, v[r][j].y * gg[j].y); w.y = pk2(v[r][j].z * gg[j].z, v[r][j].w * gg[j].w); o8[64 * j] = w; }
;         s2 = wave_sum(s2); if (lane < 16) rss[(m + r * rs) * 16 + lane] = lane == 0 ? s2 : 0.f; }
; __global__ void __launch_bounds__(NWAVES * 64, 2) mk_fwd(Args args) {
;     ...
;             for (int m = gw; m < M; m += 4 * NGW) gain_rows4_bf16(x_in, ap->in[1], HB, (float*)(ws + WS_RSS), (size_t)m, (size_t)NGW, lane);
.LBB0_447:
	s_cmp_eq_u32 s98, 2
	s_cbranch_scc1 .LBB0_458
	s_cmpk_gt_i32 s30, 0x7fff
	s_cbranch_scc1 .LBB0_458
	s_load_dwordx2 s[2:3], s[0:1], 0x8
	v_lshlrev_b32_e32 v208, 4, v217
	s_ashr_i32 s31, s30, 31
	s_ashr_i32 s43, s42, 31
	s_lshl_b64 s[6:7], s[30:31], 6
	s_waitcnt vmcnt(3) lgkmcnt(0)
	v_lshl_add_u64 v[68:69], s[2:3], 0, v[208:209]
	s_lshl_b32 s2, s90, 5
	v_cmp_lt_i32_e32 vcc, v247, v246
	s_add_u32 s10, s6, 0x4e00000
	s_addc_u32 s11, s7, 0
	v_cndmask_b32_e32 v0, v245, v247, vcc
	v_cmp_lt_i32_e32 vcc, v248, v246
	s_ashr_i32 s3, s2, 31
	v_lshlrev_b32_e32 v88, 2, v0
	v_cndmask_b32_e32 v0, v245, v248, vcc
	v_cmp_lt_i32_e32 vcc, v249, v246
	s_lshl_b64 s[6:7], s[2:3], 6
	s_lshl_b64 s[8:9], s[30:31], 11
	v_lshlrev_b32_e32 v89, 2, v0
	v_cndmask_b32_e32 v0, v245, v249, vcc
	v_cmp_lt_i32_e32 vcc, v250, v246
	s_add_u32 s8, s8, 0x7000000
	v_lshlrev_b32_e32 v90, 2, v0
	v_cndmask_b32_e32 v0, v245, v250, vcc
	v_cmp_lt_i32_e32 vcc, v251, v246
	s_addc_u32 s9, s9, 0
	v_lshlrev_b32_e32 v91, 2, v0
	v_cndmask_b32_e32 v0, v245, v251, vcc
	v_cmp_lt_i32_e32 vcc, v252, v246
	v_lshl_or_b32 v72, v217, 3, s8
	v_mov_b32_e32 v73, s9
	s_lshl_b64 s[8:9], s[2:3], 11
	s_lshl_b64 s[12:13], s[42:43], 7
	s_waitcnt vmcnt(2)
	v_lshlrev_b32_e32 v92, 2, v0
	v_cndmask_b32_e32 v0, v245, v252, vcc
	s_add_u32 s12, s10, s12
	v_lshlrev_b32_e32 v93, 2, v0
	v_lshlrev_b32_e32 v0, 2, v217
	v_mov_b32_e32 v1, v209
	s_addc_u32 s13, s11, s13
	v_lshl_add_u64 v[74:75], s[12:13], 0, v[0:1]
	s_mul_i32 s13, s42, 0xc0
	v_lshl_add_u64 v[70:71], s[10:11], 0, v[0:1]
	s_mul_hi_i32 s12, s42, 0xc0
	s_add_u32 s10, s10, s13
	s_addc_u32 s11, s11, s12
	s_waitcnt vmcnt(1)
	v_lshl_add_u64 v[76:77], s[10:11], 0, v[0:1]
	s_add_u32 s10, s42, s30
	s_addc_u32 s11, s43, s31
	s_lshl_b64 s[10:11], s[10:11], 6
	s_add_u32 s10, s10, 0x4e00000
	s_addc_u32 s11, s11, 0
	v_lshl_add_u64 v[78:79], s[10:11], 0, v[0:1]
	s_lshl_b64 s[10:11], s[30:31], 12
	v_readlane_b32 s12, v254, 27
	v_readlane_b32 s13, v254, 28
	s_add_u32 s10, s12, s10
	s_addc_u32 s11, s13, s11
	v_cmp_gt_u32_e32 vcc, 16, v217
	v_cmp_eq_u32_e64 s[4:5], 0, v217
	v_lshl_add_u64 v[80:81], s[10:11], 0, v[208:209]
	s_lshl_b64 s[10:11], s[2:3], 12
	s_lshl_b64 s[12:13], s[42:43], 12
	s_lshl_b64 s[20:21], s[42:43], 11
	s_branch .LBB0_450

; __global__ void __launch_bounds__(NWAVES * 64, 2) mk_fwd(Args args) {
;     ...
;             for (int it = gw; it < DEPTH * I_L; it += NGW) {
;                 const int l = it / I_L; int r = it - l * I_L; bf16* wl = (bf16*)(ws + WS_W + (size_t)l * WL_STRIDE);
;                 if (r < I_IN) { transpose_item(ap->in[2] + (size_t)l * DM * NIN, DM, NIN, (bf16*)((unsigned char*)wl + WO_IN), false, scr, r, lane); continue; } r -= I_IN;
;                 if (r < I_G) { transpose_item(ap->in[3] + (size_t)l * DM * NGATE, DM, NGATE, (bf16*)((unsigned char*)wl + WO_G), false, scr, r, lane); continue; } r -= I_G;
;                 if (r < I_S) { transpose_item(ap->in[13] + (size_t)l * DM * DM, DM, DM, (bf16*)((unsigned char*)wl + WO_A), false, scr, r, lane); continue; } r -= I_S;
;                 if (r < I_S) { transpose_item(ap->in[14] + (size_t)l * DM * DM, DM, DM, (bf16*)((unsigned char*)wl + WO_B), false, scr, r, lane); continue; } r -= I_S;
;                 if (r < I_S) { transpose_item(ap->in[15] + (size_t)l * DM * DM, DM, DM, (bf16*)((unsigned char*)wl + WO_O), false, scr, r, lane); continue; } r -= I_S;
;                 if (r < I_UP) { transpose_item(ap->in[17] + (size_t)l * DM * NUP, DM, NUP, (bf16*)((unsigned char*)wl + WO_UP), true, scr, r, lane); continue; } r -= I_UP;
;                 transpose_item(ap->in[20] + (size_t)l * DFF * DM, DFF, DM, (bf16*)((unsigned char*)wl + WO_DN), false, scr, r, lane);
;             }
;             for (int m = gw; m < M; m += 4 * NGW) gain_rows4_bf16(x_in, ap->in[1], HB, (float*)(ws + WS_RSS), (size_t)m, (size_t)NGW, lane);
.LBB0_458:
	s_cmp_lg_u32 s98, 1
	s_cbranch_scc1 .Lprep_cont
	s_mov_b32 s98, 2
	s_mov_b32 s30, s99
	s_branch .LBB0_406
